# ADIFF fast path restructured as QK-ahead software pipeline: next tile QK MFMAs issued before this tile PV, exps in place during PV, K/V frags double-buffered
# speedup vs baseline: 1.0500x; 1.0500x over previous
; __device__ __forceinline__ void diff_attn_phase(const Params& p, LAS unsigned char* lds) {
;     ...
;         auto issue = [&](int ch, int stg) {
;             const char* kg = (const char*)(kp + (tokb + 64 * ch) * ld); const char* vg = (const char*)(vp + (tokb + 64 * ch) * ld);
;             LAS unsigned char* sb = lds + stg * STG;
; #pragma unroll
;             for (int i = 0; i < 2; ++i) { unsigned o = doff[i]; asm volatile("" : "+v"(o));
;                 __builtin_amdgcn_global_load_lds((const void*)(kg + o), (LAS void*)(sb + dlds[i]), 16, 0, 0);
;                 __builtin_amdgcn_global_load_lds((const void*)(vg + o), (LAS void*)(sb + 16384 + dlds[i]), 16, 0, 0); }
;         };
;         issue(0, 0); issue(1, 1);
;         int s_cur = 0, s_nn = 2;
;         for (int ch = 0; ch < NCH; ++ch) {
;             if (ch + 1 < NCH) asm volatile("s_waitcnt vmcnt(4)" ::: "memory"); else asm volatile("s_waitcnt vmcnt(0)" ::: "memory");
;             __builtin_amdgcn_s_barrier(); asm volatile("" ::: "memory");
;             if (ch + 2 < NCH) issue(ch + 2, s_nn);
;             const LAS unsigned char* Ksb = lds + s_cur * STG; const LAS unsigned char* Vsb = Ksb + 16384;
;             s_nn = s_cur; s_cur = (s_cur == 2) ? 0 : s_cur + 1;
; #pragma clang loop unroll(disable)
;             for (int u = 0; u < 2; ++u) {
;                 const LAS unsigned char* Ku = Ksb + u * 8192; const LAS unsigned char* Vu = Vsb + u * 8192;
;                 int kxl = kx, vb0l = vb0, vb1l = vb1; asm volatile("" : "+v"(kxl), "+v"(vb0l), "+v"(vb1l));
;                 bf16x8 kf[4];
; #pragma unroll
;                 for (int ks = 0; ks < 4; ++ks) kf[ks] = *(const LAS bf16x8*)(Ku + kbase + (kxl ^ (32 * ks)));
;                 bf16x8 P[2][2];
; #pragma unroll
;                 for (int r = 0; r < 2; ++r) {
;                     f32x16 S;
; #pragma unroll
;                     for (int i = 0; i < 16; ++i) S[i] = 0.f;
; #pragma unroll
;                     for (int ks = 0; ks < 4; ++ks) S = __builtin_amdgcn_mfma_f32_32x32x16_bf16(kf[ks], qf[r][ks], S, 0, 0, 0);
;                     S = __builtin_amdgcn_mfma_f32_32x32x16_bf16(kone, qm[r], S, 0, 0, 0);
; #pragma unroll
;                     for (int i = 0; i < 16; ++i) S[i] = __builtin_amdgcn_exp2f(S[i]);
;                     l[r] += sum16(S);
;                     P[r][0] = pack8(S, 0); P[r][1] = pack8(S, 8);
.Lfa_entry:
	s_waitcnt lgkmcnt(0)
	v_readfirstlane_b32 s34, v242
	s_movk_i32 s47, 0x60
	s_waitcnt vmcnt(4)
	s_barrier
	s_add_i32 s2, s29, 2
	s_lshl_b32 s10, s2, 6
	s_add_u32 s10, s26, s10
	s_addc_u32 s11, s27, 0
	s_lshl_b64 s[10:11], s[10:11], 13
	s_add_u32 s42, s25, s10
	s_addc_u32 s43, s28, s11
	s_add_u32 s10, s22, s10
	s_addc_u32 s11, s23, s11
	s_and_b32 s2, s2, 3
	s_lshl_b32 s2, s2, 15
	s_add_i32 s2, s2, s34
	s_mov_b32 m0, s2
	s_add_i32 s35, s2, 0x4000
	global_load_lds_dwordx4 v241, s[42:43]
	s_mov_b32 m0, s35
	s_add_i32 s35, s2, 0x2000
	global_load_lds_dwordx4 v241, s[10:11]
	s_mov_b32 m0, s35
	s_add_i32 s35, s2, 0x6000
	global_load_lds_dwordx4 v243, s[42:43]
	s_mov_b32 m0, s35
	s_nop 0
	global_load_lds_dwordx4 v243, s[10:11]
	v_mov_b32_e32 v1, v245
	v_mov_b32_e32 v234, v247
	v_mov_b32_e32 v235, v248
	v_xor_b32_e32 v237, 64, v247
	v_xor_b32_e32 v236, 64, v248
	v_xor_b32_e32 v238, 0x80, v247
	v_xor_b32_e32 v239, 0x80, v248
	v_xor_b32_e32 v250, 0xc0, v247
	v_xor_b32_e32 v251, 0xc0, v248
	v_add_u32_e32 v198, v246, v1
	ds_read_b128 v[198:201], v198
	v_xad_u32 v202, v246, 32, v1
	ds_read_b128 v[202:205], v202
	s_waitcnt lgkmcnt(1)
	v_mfma_f32_32x32x16_bf16 v[146:161], v[198:201], v[166:169], 0
	v_mfma_f32_32x32x16_bf16 v[130:145], v[198:201], v[182:185], 0
	v_xad_u32 v198, v246, 64, v1
	ds_read_b128 v[198:201], v198
	s_waitcnt lgkmcnt(1)
	v_mfma_f32_32x32x16_bf16 v[146:161], v[202:205], v[170:173], v[146:161]
	v_mfma_f32_32x32x16_bf16 v[130:145], v[202:205], v[186:189], v[130:145]
	v_xad_u32 v202, v246, s47, v1
	ds_read_b128 v[202:205], v202
	s_waitcnt lgkmcnt(1)
	v_mfma_f32_32x32x16_bf16 v[146:161], v[198:201], v[174:177], v[146:161]
	v_mfma_f32_32x32x16_bf16 v[130:145], v[198:201], v[190:193], v[130:145]
	s_waitcnt lgkmcnt(0)
	v_mfma_f32_32x32x16_bf16 v[146:161], v[202:205], v[178:181], v[146:161]
	v_mfma_f32_32x32x16_bf16 v[130:145], v[202:205], v[194:197], v[130:145]
	ds_read_b64_tr_b16 v[208:209], v234 offset:16384
	ds_read_b64_tr_b16 v[210:211], v235 offset:16384
	v_add_u32_e32 v198, v246, v1
	ds_read_b128 v[198:201], v198 offset:8192
	v_xad_u32 v202, v246, 32, v1
	ds_read_b128 v[202:205], v202 offset:8192
	s_nop 7
	v_exp_f32_e32 v146, v146
	v_exp_f32_e32 v130, v130
	v_exp_f32_e32 v147, v147
	v_exp_f32_e32 v131, v131
	v_add_f32_e32 v213, v213, v146
	v_add_f32_e32 v212, v212, v130
	v_add_f32_e32 v213, v213, v147
	v_add_f32_e32 v212, v212, v131
	v_exp_f32_e32 v148, v148
	v_exp_f32_e32 v132, v132
	v_exp_f32_e32 v149, v149
	v_exp_f32_e32 v133, v133
	v_add_f32_e32 v213, v213, v148
	v_add_f32_e32 v212, v212, v132
	v_add_f32_e32 v213, v213, v149
	v_add_f32_e32 v212, v212, v133
	v_exp_f32_e32 v150, v150
	v_exp_f32_e32 v134, v134
	v_exp_f32_e32 v151, v151
	v_exp_f32_e32 v135, v135
	v_add_f32_e32 v213, v213, v150
	v_add_f32_e32 v212, v212, v134
	v_add_f32_e32 v213, v213, v151
	v_add_f32_e32 v212, v212, v135
	v_exp_f32_e32 v152, v152
	v_exp_f32_e32 v136, v136
	v_exp_f32_e32 v153, v153
	v_exp_f32_e32 v137, v137
	v_add_f32_e32 v213, v213, v152
	v_add_f32_e32 v212, v212, v136
	v_add_f32_e32 v213, v213, v153
	v_add_f32_e32 v212, v212, v137
	v_cvt_pk_bf16_f32 v214, v146, v147
	v_cvt_pk_bf16_f32 v218, v130, v131
	v_cvt_pk_bf16_f32 v215, v148, v149
	v_cvt_pk_bf16_f32 v219, v132, v133
	v_cvt_pk_bf16_f32 v216, v150, v151
	v_cvt_pk_bf16_f32 v220, v134, v135
	v_cvt_pk_bf16_f32 v217, v152, v153
	v_cvt_pk_bf16_f32 v221, v136, v137
	v_exp_f32_e32 v154, v154
	v_exp_f32_e32 v138, v138
	v_exp_f32_e32 v155, v155
	v_exp_f32_e32 v139, v139
	v_add_f32_e32 v213, v213, v154
	v_add_f32_e32 v212, v212, v138
	v_add_f32_e32 v213, v213, v155
	v_add_f32_e32 v212, v212, v139
	v_exp_f32_e32 v156, v156
	v_exp_f32_e32 v140, v140
	v_exp_f32_e32 v157, v157
	v_exp_f32_e32 v141, v141
	v_add_f32_e32 v213, v213, v156
	v_add_f32_e32 v212, v212, v140
	v_add_f32_e32 v213, v213, v157
	v_add_f32_e32 v212, v212, v141
	v_exp_f32_e32 v158, v158
	v_exp_f32_e32 v142, v142
	v_exp_f32_e32 v159, v159
	v_exp_f32_e32 v143, v143
	v_add_f32_e32 v213, v213, v158
	v_add_f32_e32 v212, v212, v142
	v_add_f32_e32 v213, v213, v159
	v_add_f32_e32 v212, v212, v143
	v_exp_f32_e32 v160, v160
	v_exp_f32_e32 v144, v144
	v_exp_f32_e32 v161, v161
	v_exp_f32_e32 v145, v145
	v_add_f32_e32 v213, v213, v160
	v_add_f32_e32 v212, v212, v144
	v_add_f32_e32 v213, v213, v161
	v_add_f32_e32 v212, v212, v145
	v_cvt_pk_bf16_f32 v222, v154, v155
	v_cvt_pk_bf16_f32 v226, v138, v139
	v_cvt_pk_bf16_f32 v223, v156, v157
	v_cvt_pk_bf16_f32 v227, v140, v141
	v_cvt_pk_bf16_f32 v224, v158, v159
	v_cvt_pk_bf16_f32 v228, v142, v143
	v_cvt_pk_bf16_f32 v225, v160, v161
	v_cvt_pk_bf16_f32 v229, v144, v145
; #define LAS __attribute__((address_space(3)))
; __device__ __forceinline__ void diff_attn_phase(const Params& p, LAS unsigned char* lds) {
;     ...
;             for (int u = 0; u < 2; ++u) {
;                 const LAS unsigned char* Ku = Ksb + u * 8192; const LAS unsigned char* Vu = Vsb + u * 8192;
;                 int kxl = kx, vb0l = vb0, vb1l = vb1; asm volatile("" : "+v"(kxl), "+v"(vb0l), "+v"(vb1l));
;                 bf16x8 kf[4];
; #pragma unroll
;                 for (int ks = 0; ks < 4; ++ks) kf[ks] = *(const LAS bf16x8*)(Ku + kbase + (kxl ^ (32 * ks)));
;                 bf16x8 P[2][2];
; #pragma unroll
;                 for (int r = 0; r < 2; ++r) {
;                     f32x16 S;
; #pragma unroll
;                     for (int i = 0; i < 16; ++i) S[i] = 0.f;
; #pragma unroll
;                     for (int ks = 0; ks < 4; ++ks) S = __builtin_amdgcn_mfma_f32_32x32x16_bf16(kf[ks], qf[r][ks], S, 0, 0, 0);
;                     S = __builtin_amdgcn_mfma_f32_32x32x16_bf16(kone, qm[r], S, 0, 0, 0);
; #pragma unroll
;                     for (int i = 0; i < 16; ++i) S[i] = __builtin_amdgcn_exp2f(S[i]);
;                     l[r] += sum16(S);
;                     P[r][0] = pack8(S, 0); P[r][1] = pack8(S, 8);
;                 }
; #pragma unroll
;                 for (int t = 0; t < 4; ++t) {
;                     const LAS unsigned char* a0 = Vu + (vb0l ^ (64 * t)); const LAS unsigned char* a1 = Vu + (vb1l ^ (64 * t));
;                     const bf16x8 v0 = tr_pair(a0, a1), v1 = tr_pair(a0 + 4096, a1 + 4096);
;                     O[0][t] = __builtin_amdgcn_mfma_f32_32x32x16_bf16(v0, P[0][0], O[0][t], 0, 0, 0);
;                     O[1][t] = __builtin_amdgcn_mfma_f32_32x32x16_bf16(v0, P[1][0], O[1][t], 0, 0, 0);
;                     O[0][t] = __builtin_amdgcn_mfma_f32_32x32x16_bf16(v1, P[0][1], O[0][t], 0, 0, 0);
;                     O[1][t] = __builtin_amdgcn_mfma_f32_32x32x16_bf16(v1, P[1][1], O[1][t], 0, 0, 0);
;                 }
.Lfb_loop:
	s_waitcnt lgkmcnt(1)
	v_mfma_f32_32x32x16_bf16 v[146:161], v[198:201], v[166:169], 0
	v_mfma_f32_32x32x16_bf16 v[130:145], v[198:201], v[182:185], 0
	v_xad_u32 v198, v246, 64, v1
	ds_read_b128 v[198:201], v198 offset:8192
	s_waitcnt lgkmcnt(1)
	v_mfma_f32_32x32x16_bf16 v[146:161], v[202:205], v[170:173], v[146:161]
	v_mfma_f32_32x32x16_bf16 v[130:145], v[202:205], v[186:189], v[130:145]
	v_xad_u32 v202, v246, s47, v1
	ds_read_b128 v[202:205], v202 offset:8192
	ds_read_b64_tr_b16 v[230:231], v237 offset:16384
	ds_read_b64_tr_b16 v[232:233], v236 offset:16384
	s_waitcnt lgkmcnt(3)
	v_mfma_f32_32x32x16_bf16 v[146:161], v[198:201], v[174:177], v[146:161]
	v_mfma_f32_32x32x16_bf16 v[130:145], v[198:201], v[190:193], v[130:145]
	s_waitcnt lgkmcnt(2)
	v_mfma_f32_32x32x16_bf16 v[146:161], v[202:205], v[178:181], v[146:161]
	v_mfma_f32_32x32x16_bf16 v[130:145], v[202:205], v[194:197], v[130:145]
	v_mfma_f32_32x32x16_bf16 v[114:129], v[208:211], v[214:217], v[114:129]
	v_mfma_f32_32x32x16_bf16 v[50:65], v[208:211], v[218:221], v[50:65]
	ds_read_b64_tr_b16 v[208:209], v238 offset:16384
	ds_read_b64_tr_b16 v[210:211], v239 offset:16384
	s_waitcnt lgkmcnt(2)
	v_mfma_f32_32x32x16_bf16 v[98:113], v[230:233], v[214:217], v[98:113]
	v_mfma_f32_32x32x16_bf16 v[34:49], v[230:233], v[218:221], v[34:49]
	ds_read_b64_tr_b16 v[230:231], v250 offset:16384
	ds_read_b64_tr_b16 v[232:233], v251 offset:16384
	s_waitcnt lgkmcnt(2)
	v_mfma_f32_32x32x16_bf16 v[82:97], v[208:211], v[214:217], v[82:97]
	v_mfma_f32_32x32x16_bf16 v[18:33], v[208:211], v[218:221], v[18:33]
	ds_read_b64_tr_b16 v[208:209], v234 offset:20480
	ds_read_b64_tr_b16 v[210:211], v235 offset:20480
	v_exp_f32_e32 v146, v146
	v_exp_f32_e32 v130, v130
	v_exp_f32_e32 v147, v147
	v_exp_f32_e32 v131, v131
	v_add_f32_e32 v213, v213, v146
	v_add_f32_e32 v212, v212, v130
	v_add_f32_e32 v213, v213, v147
	s_waitcnt lgkmcnt(2)
	v_mfma_f32_32x32x16_bf16 v[66:81], v[230:233], v[214:217], v[66:81]
	v_add_f32_e32 v212, v212, v131
	v_exp_f32_e32 v148, v148
	v_exp_f32_e32 v132, v132
	v_exp_f32_e32 v149, v149
	v_exp_f32_e32 v133, v133
	v_add_f32_e32 v213, v213, v148
	v_add_f32_e32 v212, v212, v132
	v_mfma_f32_32x32x16_bf16 v[2:17], v[230:233], v[218:221], v[2:17]
	ds_read_b64_tr_b16 v[230:231], v237 offset:20480
	ds_read_b64_tr_b16 v[232:233], v236 offset:20480
	v_add_f32_e32 v213, v213, v149
	v_add_f32_e32 v212, v212, v133
	v_exp_f32_e32 v150, v150
	v_exp_f32_e32 v134, v134
	v_exp_f32_e32 v151, v151
	v_exp_f32_e32 v135, v135
	v_add_f32_e32 v213, v213, v150
	s_waitcnt lgkmcnt(2)
	v_mfma_f32_32x32x16_bf16 v[114:129], v[208:211], v[222:225], v[114:129]
	v_add_f32_e32 v212, v212, v134
	v_add_f32_e32 v213, v213, v151
	v_add_f32_e32 v212, v212, v135
	v_exp_f32_e32 v152, v152
	v_exp_f32_e32 v136, v136
	v_exp_f32_e32 v153, v153
	v_exp_f32_e32 v137, v137
	v_mfma_f32_32x32x16_bf16 v[50:65], v[208:211], v[226:229], v[50:65]
	ds_read_b64_tr_b16 v[208:209], v238 offset:20480
	ds_read_b64_tr_b16 v[210:211], v239 offset:20480
	v_add_f32_e32 v213, v213, v152
	v_add_f32_e32 v212, v212, v136
	v_add_f32_e32 v213, v213, v153
	v_add_f32_e32 v212, v212, v137
	v_cvt_pk_bf16_f32 v214, v146, v147
	v_cvt_pk_bf16_f32 v218, v130, v131
	v_cvt_pk_bf16_f32 v215, v148, v149
	v_cvt_pk_bf16_f32 v219, v132, v133
	v_cvt_pk_bf16_f32 v216, v150, v151
	v_cvt_pk_bf16_f32 v220, v134, v135
	v_cvt_pk_bf16_f32 v217, v152, v153
	v_cvt_pk_bf16_f32 v221, v136, v137
	s_waitcnt lgkmcnt(2)
	v_mfma_f32_32x32x16_bf16 v[98:113], v[230:233], v[222:225], v[98:113]
	v_exp_f32_e32 v154, v154
	v_exp_f32_e32 v138, v138
	v_exp_f32_e32 v155, v155
	v_exp_f32_e32 v139, v139
	v_add_f32_e32 v213, v213, v154
	v_add_f32_e32 v212, v212, v138
	v_add_f32_e32 v213, v213, v155
	v_mfma_f32_32x32x16_bf16 v[34:49], v[230:233], v[226:229], v[34:49]
	ds_read_b64_tr_b16 v[230:231], v250 offset:20480
	ds_read_b64_tr_b16 v[232:233], v251 offset:20480
	v_add_f32_e32 v212, v212, v139
	v_exp_f32_e32 v156, v156
	v_exp_f32_e32 v140, v140
	v_exp_f32_e32 v157, v157
	v_exp_f32_e32 v141, v141
	v_add_f32_e32 v213, v213, v156
	v_add_f32_e32 v212, v212, v140
	s_waitcnt lgkmcnt(2)
	v_mfma_f32_32x32x16_bf16 v[82:97], v[208:211], v[222:225], v[82:97]
	v_add_f32_e32 v213, v213, v157
	v_add_f32_e32 v212, v212, v141
	v_exp_f32_e32 v158, v158
	v_exp_f32_e32 v142, v142
	v_exp_f32_e32 v159, v159
	v_exp_f32_e32 v143, v143
	v_add_f32_e32 v213, v213, v158
	v_mfma_f32_32x32x16_bf16 v[18:33], v[208:211], v[226:229], v[18:33]
	v_add_f32_e32 v212, v212, v142
	v_add_f32_e32 v213, v213, v159
	v_add_f32_e32 v212, v212, v143
	v_exp_f32_e32 v160, v160
	v_exp_f32_e32 v144, v144
	v_exp_f32_e32 v161, v161
	v_exp_f32_e32 v145, v145
	s_waitcnt lgkmcnt(0)
	v_mfma_f32_32x32x16_bf16 v[66:81], v[230:233], v[222:225], v[66:81]
	v_add_f32_e32 v213, v213, v160
	v_add_f32_e32 v212, v212, v144
	v_add_f32_e32 v213, v213, v161
	v_add_f32_e32 v212, v212, v145
	v_mfma_f32_32x32x16_bf16 v[2:17], v[230:233], v[226:229], v[2:17]
	v_cvt_pk_bf16_f32 v222, v154, v155
	v_cvt_pk_bf16_f32 v226, v138, v139
	v_cvt_pk_bf16_f32 v223, v156, v157
	v_cvt_pk_bf16_f32 v227, v140, v141
	v_cvt_pk_bf16_f32 v224, v158, v159
	v_cvt_pk_bf16_f32 v228, v142, v143
	v_cvt_pk_bf16_f32 v225, v160, v161
	v_cvt_pk_bf16_f32 v229, v144, v145
	ds_read_b64_tr_b16 v[208:209], v234 offset:24576
	ds_read_b64_tr_b16 v[210:211], v235 offset:24576
	s_cmpk_eq_u32 s29, 0x7f
	s_cbranch_scc1 .Lfb_tail
	s_cmpk_eq_u32 s29, 0x7e
	s_cbranch_scc1 .Lfb_w0
	s_waitcnt vmcnt(4)
	s_branch .Lfb_w1

; #define LAS __attribute__((address_space(3)))
; __device__ __forceinline__ void diff_attn_phase(const Params& p, LAS unsigned char* lds) {
;     ...
;         for (int ch = 0; ch < NCH; ++ch) {
;             if (ch + 1 < NCH) asm volatile("s_waitcnt vmcnt(4)" ::: "memory"); else asm volatile("s_waitcnt vmcnt(0)" ::: "memory");
;             __builtin_amdgcn_s_barrier(); asm volatile("" ::: "memory");
;             if (ch + 2 < NCH) issue(ch + 2, s_nn);
;             const LAS unsigned char* Ksb = lds + s_cur * STG; const LAS unsigned char* Vsb = Ksb + 16384;
;             s_nn = s_cur; s_cur = (s_cur == 2) ? 0 : s_cur + 1;
; #pragma clang loop unroll(disable)
;             for (int u = 0; u < 2; ++u) {
;                 const LAS unsigned char* Ku = Ksb + u * 8192; const LAS unsigned char* Vu = Vsb + u * 8192;
;                 int kxl = kx, vb0l = vb0, vb1l = vb1; asm volatile("" : "+v"(kxl), "+v"(vb0l), "+v"(vb1l));
;                 bf16x8 kf[4];
; #pragma unroll
;                 for (int ks = 0; ks < 4; ++ks) kf[ks] = *(const LAS bf16x8*)(Ku + kbase + (kxl ^ (32 * ks)));
;                 bf16x8 P[2][2];
; #pragma unroll
;                 for (int r = 0; r < 2; ++r) {
;                     f32x16 S;
; #pragma unroll
;                     for (int i = 0; i < 16; ++i) S[i] = 0.f;
; #pragma unroll
;                     for (int ks = 0; ks < 4; ++ks) S = __builtin_amdgcn_mfma_f32_32x32x16_bf16(kf[ks], qf[r][ks], S, 0, 0, 0);
;                     S = __builtin_amdgcn_mfma_f32_32x32x16_bf16(kone, qm[r], S, 0, 0, 0);
; #pragma unroll
;                     for (int i = 0; i < 16; ++i) S[i] = __builtin_amdgcn_exp2f(S[i]);
;                     l[r] += sum16(S);
;                     P[r][0] = pack8(S, 0); P[r][1] = pack8(S, 8);
;                 }
; #pragma unroll
;                 for (int t = 0; t < 4; ++t) {
;                     const LAS unsigned char* a0 = Vu + (vb0l ^ (64 * t)); const LAS unsigned char* a1 = Vu + (vb1l ^ (64 * t));
;                     const bf16x8 v0 = tr_pair(a0, a1), v1 = tr_pair(a0 + 4096, a1 + 4096);
;                     O[0][t] = __builtin_amdgcn_mfma_f32_32x32x16_bf16(v0, P[0][0], O[0][t], 0, 0, 0);
;                     O[1][t] = __builtin_amdgcn_mfma_f32_32x32x16_bf16(v0, P[1][0], O[1][t], 0, 0, 0);
;                     O[0][t] = __builtin_amdgcn_mfma_f32_32x32x16_bf16(v1, P[0][1], O[0][t], 0, 0, 0);
.Lfb_w1:
	s_barrier
	s_cmpk_gt_u32 s29, 0x7c
	s_cbranch_scc1 .Lfb_nodma
	s_add_i32 s2, s29, 3
	s_lshl_b32 s10, s2, 6
	s_add_u32 s10, s26, s10
	s_addc_u32 s11, s27, 0
	s_lshl_b64 s[10:11], s[10:11], 13
	s_add_u32 s42, s25, s10
	s_addc_u32 s43, s28, s11
	s_add_u32 s10, s22, s10
	s_addc_u32 s11, s23, s11
	s_and_b32 s2, s2, 3
	s_lshl_b32 s2, s2, 15
	s_add_i32 s2, s2, s34
	s_mov_b32 m0, s2
	s_add_i32 s35, s2, 0x4000
	global_load_lds_dwordx4 v241, s[42:43]
	s_mov_b32 m0, s35
	s_add_i32 s35, s2, 0x2000
	global_load_lds_dwordx4 v241, s[10:11]
	s_mov_b32 m0, s35
	s_add_i32 s35, s2, 0x6000
	global_load_lds_dwordx4 v243, s[42:43]
	s_mov_b32 m0, s35
	s_nop 0
	global_load_lds_dwordx4 v243, s[10:11]
.Lfb_nodma:
	s_add_i32 s2, s29, 1
	s_and_b32 s2, s2, 3
	s_mov_b32 s37, 0x8000
	s_cmp_eq_u32 s2, 0
	s_cselect_b32 s37, 0xfffe8000, s37
	v_add_u32_e32 v1, s37, v1
	v_add_u32_e32 v198, v246, v1
	ds_read_b128 v[198:201], v198
	v_xad_u32 v202, v246, 32, v1
	ds_read_b128 v[202:205], v202
	s_waitcnt lgkmcnt(1)
	v_mfma_f32_32x32x16_bf16 v[146:161], v[198:201], v[166:169], 0
	v_mfma_f32_32x32x16_bf16 v[130:145], v[198:201], v[182:185], 0
	v_xad_u32 v198, v246, 64, v1
	ds_read_b128 v[198:201], v198
	s_waitcnt lgkmcnt(1)
	v_mfma_f32_32x32x16_bf16 v[146:161], v[202:205], v[170:173], v[146:161]
	v_mfma_f32_32x32x16_bf16 v[130:145], v[202:205], v[186:189], v[130:145]
	v_xad_u32 v202, v246, s47, v1
	ds_read_b128 v[202:205], v202
	ds_read_b64_tr_b16 v[230:231], v237 offset:24576
	ds_read_b64_tr_b16 v[232:233], v236 offset:24576
	s_waitcnt lgkmcnt(3)
	v_mfma_f32_32x32x16_bf16 v[146:161], v[198:201], v[174:177], v[146:161]
	v_mfma_f32_32x32x16_bf16 v[130:145], v[198:201], v[190:193], v[130:145]
	s_waitcnt lgkmcnt(2)
	v_mfma_f32_32x32x16_bf16 v[146:161], v[202:205], v[178:181], v[146:161]
	v_mfma_f32_32x32x16_bf16 v[130:145], v[202:205], v[194:197], v[130:145]
	v_mfma_f32_32x32x16_bf16 v[114:129], v[208:211], v[214:217], v[114:129]
	v_mfma_f32_32x32x16_bf16 v[50:65], v[208:211], v[218:221], v[50:65]
	ds_read_b64_tr_b16 v[208:209], v238 offset:24576
	ds_read_b64_tr_b16 v[210:211], v239 offset:24576
	s_waitcnt lgkmcnt(2)
	v_mfma_f32_32x32x16_bf16 v[98:113], v[230:233], v[214:217], v[98:113]
	v_mfma_f32_32x32x16_bf16 v[34:49], v[230:233], v[218:221], v[34:49]
	ds_read_b64_tr_b16 v[230:231], v250 offset:24576
	ds_read_b64_tr_b16 v[232:233], v251 offset:24576
	s_waitcnt lgkmcnt(2)
	v_mfma_f32_32x32x16_bf16 v[82:97], v[208:211], v[214:217], v[82:97]
	v_mfma_f32_32x32x16_bf16 v[18:33], v[208:211], v[218:221], v[18:33]
	ds_read_b64_tr_b16 v[208:209], v234 offset:28672
	ds_read_b64_tr_b16 v[210:211], v235 offset:28672
	v_exp_f32_e32 v146, v146
	v_exp_f32_e32 v130, v130
	v_exp_f32_e32 v147, v147
	v_exp_f32_e32 v131, v131
	v_add_f32_e32 v213, v213, v146
	v_add_f32_e32 v212, v212, v130
	v_add_f32_e32 v213, v213, v147
	s_waitcnt lgkmcnt(2)
	v_mfma_f32_32x32x16_bf16 v[66:81], v[230:233], v[214:217], v[66:81]
	v_add_f32_e32 v212, v212, v131
	v_exp_f32_e32 v148, v148
	v_exp_f32_e32 v132, v132
	v_exp_f32_e32 v149, v149
	v_exp_f32_e32 v133, v133
	v_add_f32_e32 v213, v213, v148
	v_add_f32_e32 v212, v212, v132
	v_mfma_f32_32x32x16_bf16 v[2:17], v[230:233], v[218:221], v[2:17]
	ds_read_b64_tr_b16 v[230:231], v237 offset:28672
	ds_read_b64_tr_b16 v[232:233], v236 offset:28672
	v_add_f32_e32 v213, v213, v149
	v_add_f32_e32 v212, v212, v133
	v_exp_f32_e32 v150, v150
	v_exp_f32_e32 v134, v134
	v_exp_f32_e32 v151, v151
	v_exp_f32_e32 v135, v135
	v_add_f32_e32 v213, v213, v150
	s_waitcnt lgkmcnt(2)
	v_mfma_f32_32x32x16_bf16 v[114:129], v[208:211], v[222:225], v[114:129]
	v_add_f32_e32 v212, v212, v134
	v_add_f32_e32 v213, v213, v151
	v_add_f32_e32 v212, v212, v135
	v_exp_f32_e32 v152, v152
	v_exp_f32_e32 v136, v136
	v_exp_f32_e32 v153, v153
	v_exp_f32_e32 v137, v137
	v_mfma_f32_32x32x16_bf16 v[50:65], v[208:211], v[226:229], v[50:65]
	ds_read_b64_tr_b16 v[208:209], v238 offset:28672
	ds_read_b64_tr_b16 v[210:211], v239 offset:28672
	v_add_f32_e32 v213, v213, v152
	v_add_f32_e32 v212, v212, v136
	v_add_f32_e32 v213, v213, v153
	v_add_f32_e32 v212, v212, v137
	v_cvt_pk_bf16_f32 v214, v146, v147
	v_cvt_pk_bf16_f32 v218, v130, v131
	v_cvt_pk_bf16_f32 v215, v148, v149
	v_cvt_pk_bf16_f32 v219, v132, v133
	v_cvt_pk_bf16_f32 v216, v150, v151
	v_cvt_pk_bf16_f32 v220, v134, v135
	v_cvt_pk_bf16_f32 v217, v152, v153
	v_cvt_pk_bf16_f32 v221, v136, v137
	s_waitcnt lgkmcnt(2)
	v_mfma_f32_32x32x16_bf16 v[98:113], v[230:233], v[222:225], v[98:113]
	v_exp_f32_e32 v154, v154
	v_exp_f32_e32 v138, v138
	v_exp_f32_e32 v155, v155
	v_exp_f32_e32 v139, v139
	v_add_f32_e32 v213, v213, v154
	v_add_f32_e32 v212, v212, v138
	v_add_f32_e32 v213, v213, v155
	v_mfma_f32_32x32x16_bf16 v[34:49], v[230:233], v[226:229], v[34:49]
	ds_read_b64_tr_b16 v[230:231], v250 offset:28672
	ds_read_b64_tr_b16 v[232:233], v251 offset:28672
	v_add_f32_e32 v212, v212, v139
	v_exp_f32_e32 v156, v156
	v_exp_f32_e32 v140, v140
	v_exp_f32_e32 v157, v157
	v_exp_f32_e32 v141, v141
	v_add_f32_e32 v213, v213, v156
	v_add_f32_e32 v212, v212, v140
	s_waitcnt lgkmcnt(2)
	v_mfma_f32_32x32x16_bf16 v[82:97], v[208:211], v[222:225], v[82:97]
	v_add_f32_e32 v213, v213, v157
	v_add_f32_e32 v212, v212, v141
	v_exp_f32_e32 v158, v158
	v_exp_f32_e32 v142, v142
	v_exp_f32_e32 v159, v159
	v_exp_f32_e32 v143, v143
	v_add_f32_e32 v213, v213, v158
	v_mfma_f32_32x32x16_bf16 v[18:33], v[208:211], v[226:229], v[18:33]
	v_add_f32_e32 v212, v212, v142
	v_add_f32_e32 v213, v213, v159
	v_add_f32_e32 v212, v212, v143
	v_exp_f32_e32 v160, v160
	v_exp_f32_e32 v144, v144
	v_exp_f32_e32 v161, v161
	v_exp_f32_e32 v145, v145
	s_waitcnt lgkmcnt(0)
	v_mfma_f32_32x32x16_bf16 v[66:81], v[230:233], v[222:225], v[66:81]
	v_add_f32_e32 v213, v213, v160
	v_add_f32_e32 v212, v212, v144
	v_add_f32_e32 v213, v213, v161
	v_add_f32_e32 v212, v212, v145
	v_mfma_f32_32x32x16_bf16 v[2:17], v[230:233], v[226:229], v[2:17]
	v_cvt_pk_bf16_f32 v222, v154, v155
	v_cvt_pk_bf16_f32 v226, v138, v139
	v_cvt_pk_bf16_f32 v223, v156, v157
	v_cvt_pk_bf16_f32 v227, v140, v141
	v_cvt_pk_bf16_f32 v224, v158, v159
	v_cvt_pk_bf16_f32 v228, v142, v143
	v_cvt_pk_bf16_f32 v225, v160, v161
	v_cvt_pk_bf16_f32 v229, v144, v145
	v_add_u32_e32 v234, s37, v234
	v_add_u32_e32 v235, s37, v235
	v_add_u32_e32 v237, s37, v237
	v_add_u32_e32 v236, s37, v236
	v_add_u32_e32 v238, s37, v238
	v_add_u32_e32 v239, s37, v239
	v_add_u32_e32 v250, s37, v250
	v_add_u32_e32 v251, s37, v251
	ds_read_b64_tr_b16 v[208:209], v234 offset:16384
	ds_read_b64_tr_b16 v[210:211], v235 offset:16384
	v_add_u32_e32 v198, v246, v1
	ds_read_b128 v[198:201], v198 offset:8192
	v_xad_u32 v202, v246, 32, v1
	ds_read_b128 v[202:205], v202 offset:8192
	s_add_i32 s29, s29, 1
	s_branch .Lfb_loop
; #define LAS __attribute__((address_space(3)))
; __device__ __forceinline__ void diff_attn_phase(const Params& p, LAS unsigned char* lds) {
;     ...
; #pragma unroll
;                 for (int t = 0; t < 4; ++t) {
;                     const LAS unsigned char* a0 = Vu + (vb0l ^ (64 * t)); const LAS unsigned char* a1 = Vu + (vb1l ^ (64 * t));
;                     const bf16x8 v0 = tr_pair(a0, a1), v1 = tr_pair(a0 + 4096, a1 + 4096);
;                     O[0][t] = __builtin_amdgcn_mfma_f32_32x32x16_bf16(v0, P[0][0], O[0][t], 0, 0, 0);
;                     O[1][t] = __builtin_amdgcn_mfma_f32_32x32x16_bf16(v0, P[1][0], O[1][t], 0, 0, 0);
;                     O[0][t] = __builtin_amdgcn_mfma_f32_32x32x16_bf16(v1, P[0][1], O[0][t], 0, 0, 0);
;                     O[1][t] = __builtin_amdgcn_mfma_f32_32x32x16_bf16(v1, P[1][1], O[1][t], 0, 0, 0);
;                 }
.Lfb_tail:
	ds_read_b64_tr_b16 v[230:231], v237 offset:24576
	ds_read_b64_tr_b16 v[232:233], v236 offset:24576
	s_waitcnt lgkmcnt(2)
	v_mfma_f32_32x32x16_bf16 v[114:129], v[208:211], v[214:217], v[114:129]
	v_mfma_f32_32x32x16_bf16 v[50:65], v[208:211], v[218:221], v[50:65]
	ds_read_b64_tr_b16 v[208:209], v238 offset:24576
	ds_read_b64_tr_b16 v[210:211], v239 offset:24576
	s_waitcnt lgkmcnt(2)
	v_mfma_f32_32x32x16_bf16 v[98:113], v[230:233], v[214:217], v[98:113]
	v_mfma_f32_32x32x16_bf16 v[34:49], v[230:233], v[218:221], v[34:49]
	ds_read_b64_tr_b16 v[230:231], v250 offset:24576
	ds_read_b64_tr_b16 v[232:233], v251 offset:24576
	s_waitcnt lgkmcnt(2)
	v_mfma_f32_32x32x16_bf16 v[82:97], v[208:211], v[214:217], v[82:97]
	v_mfma_f32_32x32x16_bf16 v[18:33], v[208:211], v[218:221], v[18:33]
	ds_read_b64_tr_b16 v[208:209], v234 offset:28672
	ds_read_b64_tr_b16 v[210:211], v235 offset:28672
	s_waitcnt lgkmcnt(2)
	v_mfma_f32_32x32x16_bf16 v[66:81], v[230:233], v[214:217], v[66:81]
	v_mfma_f32_32x32x16_bf16 v[2:17], v[230:233], v[218:221], v[2:17]
	ds_read_b64_tr_b16 v[230:231], v237 offset:28672
	ds_read_b64_tr_b16 v[232:233], v236 offset:28672
	s_waitcnt lgkmcnt(2)
	v_mfma_f32_32x32x16_bf16 v[114:129], v[208:211], v[222:225], v[114:129]
	v_mfma_f32_32x32x16_bf16 v[50:65], v[208:211], v[226:229], v[50:65]
	ds_read_b64_tr_b16 v[208:209], v238 offset:28672
	ds_read_b64_tr_b16 v[210:211], v239 offset:28672
	s_waitcnt lgkmcnt(2)
	v_mfma_f32_32x32x16_bf16 v[98:113], v[230:233], v[222:225], v[98:113]
	v_mfma_f32_32x32x16_bf16 v[34:49], v[230:233], v[226:229], v[34:49]
	ds_read_b64_tr_b16 v[230:231], v250 offset:28672
	ds_read_b64_tr_b16 v[232:233], v251 offset:28672
	s_waitcnt lgkmcnt(2)
	v_mfma_f32_32x32x16_bf16 v[82:97], v[208:211], v[222:225], v[82:97]
	v_mfma_f32_32x32x16_bf16 v[18:33], v[208:211], v[226:229], v[18:33]
	s_waitcnt lgkmcnt(0)
	v_mfma_f32_32x32x16_bf16 v[66:81], v[230:233], v[222:225], v[66:81]
	v_mfma_f32_32x32x16_bf16 v[2:17], v[230:233], v[226:229], v[2:17]

; template <int HD, int DV, int HW, int MODE> ...
;     ...
;                 for (int i = 0; i < 16; ++i) { const int j = js + (i & 7) + 8 * hh + 16 * (i >> 3); const int d = qi - j; const bool ok = (d <= HW) && (d >= -HW) && (j >= 0) && (j < L); S[i] = ok ? S[i] : -INFINITY; }
.LBB0_58:
	v_mov_b32_e32 v235, 0x1400
	v_mov_b32_e32 v236, 0xff800000
	v_mov_b32_e32 v209, 1
	v_mov_b64_e32 v[210:211], 0x1ff
	v_mov_b64_e32 v[220:221], 0x7ff
